# hbkeep: each WG keeps 8 of its 16 bf16 h blocks from the P3 epilogue in VGPRs idle through seam 4 and the P4 K-loop; the P4 epilogue uses them instead of re-loading those HB blocks
# speedup vs baseline: 1.0064x; 1.0059x over previous
; __device__ __forceinline__ unsigned cvtpk(float lo, float hi) { f32x2 v = {lo, hi}; bf16x2_t b = __builtin_convertvector(v, bf16x2_t); return __builtin_bit_cast(unsigned, b); }
;     __device__ __forceinline__ void operator()(const Acc& acc, const Unit& u, int wr, int wc, int fr, int fq) const {
;     ...
;         for (int ai = 0; ai < 2; ++ai) {
;             f32x4 xv[4][2][2];
; #pragma unroll
;             for (int m = 0; m < 4; ++m) { const size_t off = (size_t)(u.pm * 256 + ai * 128 + wr * 64 + m * 16 + fr) * DM + colbase;
; #pragma unroll
;                 for (int bj = 0; bj < 2; ++bj) { xv[m][bj][0] = __builtin_nontemporal_load((const f32x4*)(x + off + 32 * bj)); xv[m][bj][1] = __builtin_nontemporal_load((const f32x4*)(x + off + 32 * bj + 4)); } }
; #pragma unroll
;             for (int m = 0; m < 4; ++m) {
;                 const int row = u.pm * 256 + ai * 128 + wr * 64 + m * 16 + fr;
;                 float ss = 0.f;
; #pragma unroll
;                 for (int bj = 0; bj < 2; ++bj) {
;                     const size_t off = (size_t)row * DM + colbase + 32 * bj;
;                     const f32x4 h0 = xv[m][bj][0] + acc[ai][bj][m][0], h1 = xv[m][bj][1] + acc[ai][bj][m][1];
;                     u32x4 w; w.x = cvtpk(h0.x, h0.y); w.y = cvtpk(h0.z, h0.w); w.z = cvtpk(h1.x, h1.y); w.w = cvtpk(h1.z, h1.w);
;                     *(u32x4*)(HB + off) = w;
;                     ss += (h0.x * h0.x + h0.y * h0.y) + (h0.z * h0.z + h0.w * h0.w) + (h1.x * h1.x + h1.y * h1.y) + (h1.z * h1.z + h1.w * h1.w);
;                 }
;                 ss = quad_sum(ss);
;                 if (fq == 0) atomicAdd(rowss + row, ss);
.LBB0_725:
	v_mov_b32_e32 v128, v200
	s_lshl_b32 s13, s22, 8
	s_or_b32 s13, s13, s86
	v_and_b32_e32 v129, 15, v128
	v_bfe_u32 v202, v128, 4, 2
	s_nop 0
	v_lshl_add_u32 v188, v202, 3, s13
	s_lshl_b32 s13, s20, 8
	s_add_i32 s13, s13, s79
	v_add_u32_e32 v192, s13, v129
	v_ashrrev_i32_e32 v189, 31, v188
	v_ashrrev_i32_e32 v193, 31, v192
	v_lshl_add_u64 v[190:191], v[188:189], 2, s[8:9]
	v_lshlrev_b64 v[128:129], 13, v[192:193]
	v_lshl_add_u64 v[128:129], v[190:191], 0, v[128:129]
	flat_load_dwordx4 v[206:209], v[128:129] nt
	flat_load_dwordx4 v[210:213], v[128:129] offset:16 nt
	flat_load_dwordx4 v[214:217], v[128:129] offset:128 nt
	flat_load_dwordx4 v[218:221], v[128:129] offset:144 nt
	v_add_u32_e32 v198, 16, v192
	v_add_u32_e32 v196, 32, v192
	v_add_u32_e32 v194, 48, v192
	v_ashrrev_i32_e32 v199, 31, v198
	v_ashrrev_i32_e32 v197, 31, v196
	v_ashrrev_i32_e32 v195, 31, v194
	v_lshlrev_b64 v[128:129], 13, v[198:199]
	v_lshlrev_b64 v[130:131], 13, v[196:197]
	v_lshlrev_b64 v[132:133], 13, v[194:195]
	v_lshl_add_u64 v[128:129], v[190:191], 0, v[128:129]
	v_lshl_add_u64 v[130:131], v[190:191], 0, v[130:131]
	v_lshl_add_u64 v[222:223], v[190:191], 0, v[132:133]
	flat_load_dwordx4 v[172:175], v[128:129] nt
	flat_load_dwordx4 v[168:171], v[128:129] offset:16 nt
	flat_load_dwordx4 v[164:167], v[128:129] offset:128 nt
	flat_load_dwordx4 v[160:163], v[128:129] offset:144 nt
	flat_load_dwordx4 v[156:159], v[130:131] nt
	flat_load_dwordx4 v[152:155], v[130:131] offset:16 nt
	flat_load_dwordx4 v[148:151], v[130:131] offset:128 nt
	flat_load_dwordx4 v[144:147], v[130:131] offset:144 nt
	flat_load_dwordx4 v[140:143], v[222:223] nt
	flat_load_dwordx4 v[136:139], v[222:223] offset:16 nt
	flat_load_dwordx4 v[132:135], v[222:223] offset:128 nt
	s_nop 0
	flat_load_dwordx4 v[128:131], v[222:223] offset:144 nt
	v_cmp_eq_u32_e32 vcc, 0, v202
	v_lshlrev_b64 v[222:223], 12, v[192:193]
	v_lshl_add_u64 v[222:223], s[10:11], 0, v[222:223]
	v_lshl_add_u64 v[222:223], v[188:189], 1, v[222:223]
	s_waitcnt vmcnt(0) lgkmcnt(0)
	v_pk_add_f32 v[126:127], v[126:127], v[208:209]
	v_pk_add_f32 v[124:125], v[124:125], v[206:207]
	v_pk_add_f32 v[118:119], v[118:119], v[216:217]
	v_pk_add_f32 v[206:207], v[116:117], v[214:215]
	v_pk_add_f32 v[120:121], v[120:121], v[210:211]
	v_pk_add_f32 v[210:211], v[112:113], v[218:219]
	v_cvt_pk_bf16_f32 v112, v124, v125
	v_cvt_pk_bf16_f32 v113, v126, v127
	v_mul_f32_e32 v125, v125, v125
	v_mul_f32_e32 v127, v127, v127
	v_cvt_pk_bf16_f32 v117, v118, v119
	v_mul_f32_e32 v202, v207, v207
	v_mul_f32_e32 v119, v119, v119
	v_pk_add_f32 v[122:123], v[122:123], v[212:213]
	v_pk_add_f32 v[208:209], v[114:115], v[220:221]
	v_cvt_pk_bf16_f32 v114, v120, v121
	v_mul_f32_e32 v121, v121, v121
	v_cvt_pk_bf16_f32 v116, v206, v207
	v_mul_f32_e32 v207, v211, v211
	v_fmac_f32_e32 v125, v124, v124
	v_fmac_f32_e32 v127, v126, v126
	v_fmac_f32_e32 v202, v206, v206
	v_fmac_f32_e32 v119, v118, v118
	v_cvt_pk_bf16_f32 v115, v122, v123
	v_mul_f32_e32 v123, v123, v123
	v_mul_f32_e32 v212, v209, v209
	v_fmac_f32_e32 v121, v120, v120
	v_fmac_f32_e32 v207, v210, v210
	v_add_f32_e32 v118, v125, v127
	v_add_f32_e32 v119, v202, v119
	v_fmac_f32_e32 v123, v122, v122
	v_fmac_f32_e32 v212, v208, v208
	v_add_f32_e32 v118, v118, v121
	v_add_f32_e32 v119, v119, v207
	v_add_f32_e32 v118, v123, v118
	v_add_f32_e32 v119, v212, v119
	v_add_f32_e32 v120, v118, v119
	ds_swizzle_b32 v121, v120 offset:swizzle(SWAP,16)
	v_cvt_pk_bf16_f32 v118, v210, v211
	v_cvt_pk_bf16_f32 v119, v208, v209
	v_mov_b64_e32 v[224:225], v[112:113]
	v_mov_b64_e32 v[226:227], v[114:115]
	flat_store_dwordx4 v[222:223], v[112:115]
	v_mov_b64_e32 v[214:215], v[116:117]
	v_mov_b64_e32 v[216:217], v[118:119]
	flat_store_dwordx4 v[222:223], v[116:119] offset:64
	s_waitcnt lgkmcnt(0)
	v_add_f32_e32 v114, v120, v121
	v_mov_b32_e32 v115, v114
	s_nop 1
	v_permlane32_swap_b32_e32 v114, v115
	v_lshl_add_u64 v[112:113], v[192:193], 2, s[6:7]
	s_and_saveexec_b64 s[20:21], vcc
	s_cbranch_execz .LBB0_727
	v_add_f32_e32 v114, v114, v115
	flat_atomic_add_f32 v[112:113], v114
.LBB0_727:
	s_or_b64 exec, exec, s[20:21]
	v_lshlrev_b64 v[114:115], 12, v[198:199]
	v_pk_add_f32 v[110:111], v[110:111], v[174:175]
	v_pk_add_f32 v[108:109], v[108:109], v[172:173]
	v_pk_add_f32 v[116:117], v[106:107], v[170:171]
	v_pk_add_f32 v[118:119], v[104:105], v[168:169]
	v_lshl_add_u64 v[114:115], s[10:11], 0, v[114:115]
	v_cvt_pk_bf16_f32 v104, v108, v109
	v_cvt_pk_bf16_f32 v105, v110, v111
	v_cvt_pk_bf16_f32 v106, v118, v119
	v_cvt_pk_bf16_f32 v107, v116, v117
	v_lshl_add_u64 v[114:115], v[188:189], 1, v[114:115]
	v_mov_b64_e32 v[228:229], v[104:105]
	v_mov_b64_e32 v[230:231], v[106:107]
	flat_store_dwordx4 v[114:115], v[104:107]
	v_pk_add_f32 v[100:101], v[100:101], v[164:165]
	v_pk_add_f32 v[102:103], v[102:103], v[166:167]
	v_mul_f32_e32 v104, v109, v109
	v_mul_f32_e32 v105, v111, v111
	v_fmac_f32_e32 v104, v108, v108
	v_fmac_f32_e32 v105, v110, v110
	v_add_f32_e32 v104, v104, v105
	v_mul_f32_e32 v105, v119, v119
	v_fmac_f32_e32 v105, v118, v118
	v_add_f32_e32 v104, v104, v105
	v_mul_f32_e32 v105, v117, v117
	v_fmac_f32_e32 v105, v116, v116
	v_add_f32_e32 v106, v105, v104
	v_pk_add_f32 v[104:105], v[98:99], v[162:163]
	v_pk_add_f32 v[98:99], v[96:97], v[160:161]
	v_mul_f32_e32 v97, v101, v101
	v_cvt_pk_bf16_f32 v96, v100, v101
	v_fmac_f32_e32 v97, v100, v100
	v_mul_f32_e32 v100, v103, v103
	v_fmac_f32_e32 v100, v102, v102
	v_add_f32_e32 v97, v97, v100
	v_mul_f32_e32 v100, v99, v99
	v_fmac_f32_e32 v100, v98, v98
	v_add_f32_e32 v97, v97, v100
	v_mul_f32_e32 v100, v105, v105
	v_fmac_f32_e32 v100, v104, v104
	v_add_f32_e32 v97, v100, v97
	v_add_f32_e32 v100, v106, v97
	ds_swizzle_b32 v101, v100 offset:swizzle(SWAP,16)
	v_cvt_pk_bf16_f32 v97, v102, v103
	v_cvt_pk_bf16_f32 v98, v98, v99
	v_cvt_pk_bf16_f32 v99, v104, v105
	v_mov_b64_e32 v[232:233], v[96:97]
	v_mov_b64_e32 v[234:235], v[98:99]
	flat_store_dwordx4 v[114:115], v[96:99] offset:64
	s_waitcnt lgkmcnt(0)
	s_nop 0
	v_add_f32_e32 v96, v100, v101
	v_mov_b32_e32 v97, v96
	s_nop 1
	v_permlane32_swap_b32_e32 v96, v97
	s_and_saveexec_b64 s[20:21], vcc
	s_cbranch_execz .LBB0_729
	v_add_f32_e32 v96, v96, v97
	flat_atomic_add_f32 v[112:113], v96 offset:64
; __device__ __forceinline__ unsigned cvtpk(float lo, float hi) { f32x2 v = {lo, hi}; bf16x2_t b = __builtin_convertvector(v, bf16x2_t); return __builtin_bit_cast(unsigned, b); }
;     __device__ __forceinline__ void operator()(const Acc& acc, const Unit& u, int wr, int wc, int fr, int fq) const {
;     ...
;             for (int m = 0; m < 4; ++m) {
;                 const int row = u.pm * 256 + ai * 128 + wr * 64 + m * 16 + fr;
;                 float ss = 0.f;
; #pragma unroll
;                 for (int bj = 0; bj < 2; ++bj) {
;                     const size_t off = (size_t)row * DM + colbase + 32 * bj;
;                     const f32x4 h0 = xv[m][bj][0] + acc[ai][bj][m][0], h1 = xv[m][bj][1] + acc[ai][bj][m][1];
;                     u32x4 w; w.x = cvtpk(h0.x, h0.y); w.y = cvtpk(h0.z, h0.w); w.z = cvtpk(h1.x, h1.y); w.w = cvtpk(h1.z, h1.w);
;                     *(u32x4*)(HB + off) = w;
;                     ss += (h0.x * h0.x + h0.y * h0.y) + (h0.z * h0.z + h0.w * h0.w) + (h1.x * h1.x + h1.y * h1.y) + (h1.z * h1.z + h1.w * h1.w);
;                 }
;                 ss = quad_sum(ss);
;                 if (fq == 0) atomicAdd(rowss + row, ss);
.LBB0_729:
	s_or_b64 exec, exec, s[20:21]
	v_lshlrev_b64 v[96:97], 12, v[196:197]
	v_pk_add_f32 v[94:95], v[94:95], v[158:159]
	v_pk_add_f32 v[92:93], v[92:93], v[156:157]
	v_pk_add_f32 v[98:99], v[90:91], v[154:155]
	v_pk_add_f32 v[100:101], v[88:89], v[152:153]
	v_lshl_add_u64 v[96:97], s[10:11], 0, v[96:97]
	v_cvt_pk_bf16_f32 v88, v92, v93
	v_cvt_pk_bf16_f32 v89, v94, v95
	v_cvt_pk_bf16_f32 v90, v100, v101
	v_cvt_pk_bf16_f32 v91, v98, v99
	v_lshl_add_u64 v[96:97], v[188:189], 1, v[96:97]
	v_mov_b64_e32 v[236:237], v[88:89]
	v_mov_b64_e32 v[238:239], v[90:91]
	flat_store_dwordx4 v[96:97], v[88:91]
	v_pk_add_f32 v[84:85], v[84:85], v[148:149]
	v_pk_add_f32 v[86:87], v[86:87], v[150:151]
	v_mul_f32_e32 v88, v93, v93
	v_mul_f32_e32 v89, v95, v95
	v_fmac_f32_e32 v88, v92, v92
	v_fmac_f32_e32 v89, v94, v94
	v_add_f32_e32 v88, v88, v89
	v_mul_f32_e32 v89, v101, v101
	v_fmac_f32_e32 v89, v100, v100
	v_add_f32_e32 v88, v88, v89
	v_mul_f32_e32 v89, v99, v99
	v_fmac_f32_e32 v89, v98, v98
	v_add_f32_e32 v90, v89, v88
	v_pk_add_f32 v[88:89], v[82:83], v[146:147]
	v_pk_add_f32 v[82:83], v[80:81], v[144:145]
	v_mul_f32_e32 v81, v85, v85
	v_cvt_pk_bf16_f32 v80, v84, v85
	v_fmac_f32_e32 v81, v84, v84
	v_mul_f32_e32 v84, v87, v87
	v_fmac_f32_e32 v84, v86, v86
	v_add_f32_e32 v81, v81, v84
	v_mul_f32_e32 v84, v83, v83
	v_fmac_f32_e32 v84, v82, v82
	v_add_f32_e32 v81, v81, v84
	v_mul_f32_e32 v84, v89, v89
	v_fmac_f32_e32 v84, v88, v88
	v_add_f32_e32 v81, v84, v81
	v_add_f32_e32 v84, v90, v81
	ds_swizzle_b32 v85, v84 offset:swizzle(SWAP,16)
	v_cvt_pk_bf16_f32 v81, v86, v87
	v_cvt_pk_bf16_f32 v82, v82, v83
	v_cvt_pk_bf16_f32 v83, v88, v89
	v_mov_b64_e32 v[240:241], v[80:81]
	v_mov_b64_e32 v[242:243], v[82:83]
	flat_store_dwordx4 v[96:97], v[80:83] offset:64
	s_waitcnt lgkmcnt(0)
	s_nop 0
	v_add_f32_e32 v80, v84, v85
	v_mov_b32_e32 v81, v80
	s_nop 1
	v_permlane32_swap_b32_e32 v80, v81
	s_and_saveexec_b64 s[20:21], vcc
	s_cbranch_execz .LBB0_731
	v_add_f32_e32 v80, v80, v81
	flat_atomic_add_f32 v[112:113], v80 offset:128
.LBB0_731:
	s_or_b64 exec, exec, s[20:21]
	v_lshlrev_b64 v[80:81], 12, v[194:195]
	v_pk_add_f32 v[78:79], v[78:79], v[142:143]
	v_pk_add_f32 v[76:77], v[76:77], v[140:141]
	v_pk_add_f32 v[82:83], v[74:75], v[138:139]
	v_pk_add_f32 v[84:85], v[72:73], v[136:137]
	v_lshl_add_u64 v[80:81], s[10:11], 0, v[80:81]
	v_cvt_pk_bf16_f32 v72, v76, v77
	v_cvt_pk_bf16_f32 v73, v78, v79
	v_cvt_pk_bf16_f32 v74, v84, v85
	v_cvt_pk_bf16_f32 v75, v82, v83
	v_lshl_add_u64 v[80:81], v[188:189], 1, v[80:81]
	v_mov_b64_e32 v[210:211], v[72:73]
	v_mov_b64_e32 v[212:213], v[74:75]
	flat_store_dwordx4 v[80:81], v[72:75]
	v_pk_add_f32 v[68:69], v[68:69], v[132:133]
	v_pk_add_f32 v[70:71], v[70:71], v[134:135]
	v_mul_f32_e32 v72, v77, v77
	v_mul_f32_e32 v73, v79, v79
	v_fmac_f32_e32 v72, v76, v76
	v_fmac_f32_e32 v73, v78, v78
	v_add_f32_e32 v72, v72, v73
	v_mul_f32_e32 v73, v85, v85
	v_fmac_f32_e32 v73, v84, v84
	v_add_f32_e32 v72, v72, v73
	v_mul_f32_e32 v73, v83, v83
	v_fmac_f32_e32 v73, v82, v82
	v_add_f32_e32 v74, v73, v72
	v_pk_add_f32 v[72:73], v[66:67], v[130:131]
	v_pk_add_f32 v[66:67], v[64:65], v[128:129]
	v_mul_f32_e32 v65, v69, v69
	v_cvt_pk_bf16_f32 v64, v68, v69
	v_fmac_f32_e32 v65, v68, v68
	v_mul_f32_e32 v68, v71, v71
	v_fmac_f32_e32 v68, v70, v70
	v_add_f32_e32 v65, v65, v68
	v_mul_f32_e32 v68, v67, v67
	v_fmac_f32_e32 v68, v66, v66
	v_add_f32_e32 v65, v65, v68
	v_mul_f32_e32 v68, v73, v73
	v_fmac_f32_e32 v68, v72, v72
	v_add_f32_e32 v65, v68, v65
	v_add_f32_e32 v68, v74, v65
	ds_swizzle_b32 v69, v68 offset:swizzle(SWAP,16)
	v_cvt_pk_bf16_f32 v65, v70, v71
	v_cvt_pk_bf16_f32 v66, v66, v67
	v_cvt_pk_bf16_f32 v67, v72, v73
	v_mov_b64_e32 v[244:245], v[64:65]
	v_mov_b64_e32 v[246:247], v[66:67]
	flat_store_dwordx4 v[80:81], v[64:67] offset:64
	s_waitcnt lgkmcnt(0)
	s_nop 0
	v_add_f32_e32 v64, v68, v69
	v_mov_b32_e32 v65, v64
	s_nop 1
	v_permlane32_swap_b32_e32 v64, v65
	s_and_saveexec_b64 s[20:21], vcc
	s_cbranch_execz .LBB0_733
	v_add_f32_e32 v64, v64, v65
	flat_atomic_add_f32 v[112:113], v64 offset:192

;     __device__ __forceinline__ void operator()(const Acc& acc, const Unit& u, int wr, int wc, int fr, int fq) const {
;         asm volatile("" : "+v"(fr), "+v"(fq));
;         const int colbase = u.pn * 256 + wc * 64 + 8 * fq;
; #pragma unroll
;         for (int ai = 0; ai < 2; ++ai) {
;             f32x4 hv[4][2][2]; u32x4 pw[4][2]; float rsv[4];
; #pragma unroll
;             for (int m = 0; m < 4; ++m) { const int row = u.pm * 256 + ai * 128 + wr * 64 + m * 16 + fr; const size_t off = (size_t)row * DM + colbase;
;                 rsv[m] = rowss[row];
; #pragma unroll
;                 for (int bj = 0; bj < 2; ++bj) { const u32x4 hw = __builtin_nontemporal_load((const u32x4*)(hin + off + 32 * bj));
;                     hv[m][bj][0] = (f32x4){bflo(hw.x), bfhi(hw.x), bflo(hw.y), bfhi(hw.y)}; hv[m][bj][1] = (f32x4){bflo(hw.z), bfhi(hw.z), bflo(hw.w), bfhi(hw.w)};
;                     pw[m][bj] = __builtin_nontemporal_load((const u32x4*)(PP + off + 32 * bj)); } }
; #pragma unroll
;             for (int m = 0; m < 4; ++m) {
;                 const int row = u.pm * 256 + ai * 128 + wr * 64 + m * 16 + fr;
;                 const float rs = rsqrtf(rsv[m] * (1.0f / DM) + EPS) * -1.4426950408889634f;
; #pragma unroll
;                 for (int bj = 0; bj < 2; ++bj) {
;                     const size_t off = (size_t)row * DM + colbase + 32 * bj;
;                     f32x4 h0 = hv[m][bj][0], h1 = hv[m][bj][1];
;                     const u32x4 p4 = pw[m][bj];
;                     const f32x4 a0 = acc[ai][bj][m][0], a1 = acc[ai][bj][m][1];
;                     h0.x += bflo(p4.x) * __builtin_amdgcn_rcpf(1.0f + __builtin_amdgcn_exp2f(a0.x * rs));
;                     h0.y += bfhi(p4.x) * __builtin_amdgcn_rcpf(1.0f + __builtin_amdgcn_exp2f(a0.y * rs));
;                     h0.z += bflo(p4.y) * __builtin_amdgcn_rcpf(1.0f + __builtin_amdgcn_exp2f(a0.z * rs));
;                     h0.w += bfhi(p4.y) * __builtin_amdgcn_rcpf(1.0f + __builtin_amdgcn_exp2f(a0.w * rs));
;                     h1.x += bflo(p4.z) * __builtin_amdgcn_rcpf(1.0f + __builtin_amdgcn_exp2f(a1.x * rs));
;                     h1.y += bfhi(p4.z) * __builtin_amdgcn_rcpf(1.0f + __builtin_amdgcn_exp2f(a1.y * rs));
;                     h1.z += bflo(p4.w) * __builtin_amdgcn_rcpf(1.0f + __builtin_amdgcn_exp2f(a1.z * rs));
.LBB0_814:
	v_mov_b64_e32 v[206:207], v[224:225]
	v_mov_b64_e32 v[208:209], v[226:227]
	v_mov_b64_e32 v[172:173], v[228:229]
	v_mov_b64_e32 v[174:175], v[230:231]
	v_mov_b64_e32 v[164:165], v[232:233]
	v_mov_b64_e32 v[166:167], v[234:235]
	v_mov_b64_e32 v[156:157], v[236:237]
	v_mov_b64_e32 v[158:159], v[238:239]
	v_mov_b64_e32 v[148:149], v[240:241]
	v_mov_b64_e32 v[150:151], v[242:243]
	v_mov_b64_e32 v[140:141], v[210:211]
	v_mov_b64_e32 v[142:143], v[212:213]
	v_mov_b32_e32 v128, v200
	s_lshl_b32 s11, s42, 8
	v_and_b32_e32 v129, 15, v128
	v_bfe_u32 v128, v128, 4, 2
	s_or_b32 s11, s11, s86
	s_nop 0
	v_lshl_add_u32 v188, v128, 3, s11
	s_lshl_b32 s11, s41, 8
	s_add_i32 s11, s11, s79
	v_add_u32_e32 v190, s11, v129
	v_ashrrev_i32_e32 v191, 31, v190
	v_lshl_add_u64 v[192:193], v[190:191], 2, s[80:81]
	flat_load_dword v226, v[192:193]
	v_ashrrev_i32_e32 v189, 31, v188
	v_lshlrev_b64 v[128:129], 11, v[190:191]
	v_lshl_add_u64 v[222:223], v[128:129], 0, v[188:189]
	v_lshlrev_b64 v[128:129], 1, v[222:223]
	v_lshl_add_u64 v[130:131], s[6:7], 0, v[128:129]
	v_lshl_add_u64 v[128:129], s[8:9], 0, v[128:129]
	flat_load_dwordx4 v[210:213], v[128:129] nt
	flat_load_dword v234, v[192:193] offset:64
	flat_load_dword v235, v[192:193] offset:128
	flat_load_dword v191, v[192:193] offset:192
	flat_load_dwordx4 v[218:221], v[128:129] offset:64 nt
	v_add_u32_e32 v132, 16, v190
	v_add_u32_e32 v134, 32, v190
	v_add_u32_e32 v136, 48, v190
	v_ashrrev_i32_e32 v133, 31, v132
	v_ashrrev_i32_e32 v135, 31, v134
	v_ashrrev_i32_e32 v137, 31, v136
	v_lshlrev_b64 v[132:133], 11, v[132:133]
	v_lshlrev_b64 v[134:135], 11, v[134:135]
	v_lshlrev_b64 v[136:137], 11, v[136:137]
	v_lshl_add_u64 v[198:199], v[132:133], 0, v[188:189]
	v_lshl_add_u64 v[196:197], v[134:135], 0, v[188:189]
	v_lshl_add_u64 v[194:195], v[136:137], 0, v[188:189]
	v_lshlrev_b64 v[132:133], 1, v[198:199]
	v_lshlrev_b64 v[134:135], 1, v[196:197]
	v_lshlrev_b64 v[136:137], 1, v[194:195]
	v_lshl_add_u64 v[128:129], s[6:7], 0, v[132:133]
	v_lshl_add_u64 v[130:131], s[8:9], 0, v[132:133]
	v_lshl_add_u64 v[132:133], s[6:7], 0, v[134:135]
	v_lshl_add_u64 v[134:135], s[8:9], 0, v[134:135]
	v_lshl_add_u64 v[138:139], s[6:7], 0, v[136:137]
	v_lshl_add_u64 v[224:225], s[8:9], 0, v[136:137]
	flat_load_dwordx4 v[168:171], v[130:131] nt
	flat_load_dwordx4 v[160:163], v[130:131] offset:64 nt
	flat_load_dwordx4 v[152:155], v[134:135] nt
	flat_load_dwordx4 v[144:147], v[134:135] offset:64 nt
	s_nop 0
	v_mov_b64_e32 v[132:133], v[244:245]
	v_mov_b64_e32 v[134:135], v[246:247]
	s_nop 0
	flat_load_dwordx4 v[136:139], v[224:225] nt
	flat_load_dwordx4 v[128:131], v[224:225] offset:64 nt
	s_waitcnt vmcnt(0) lgkmcnt(0)
	v_fmamk_f32 v224, v226, 0x3a000000, v205
	v_mul_f32_e32 v225, 0x4b800000, v224
	v_cmp_gt_f32_e32 vcc, s40, v224
	v_lshlrev_b32_e32 v228, 16, v208
	s_nop 0
	v_cndmask_b32_e32 v224, v224, v225, vcc
	v_rsq_f32_e32 v232, v224
	v_and_b32_e32 v229, 0xffff0000, v208
	v_lshlrev_b32_e32 v230, 16, v212
	v_and_b32_e32 v231, 0xffff0000, v212
	v_mul_f32_e32 v208, 0x45800000, v232
	v_cndmask_b32_e32 v208, v232, v208, vcc
	v_mul_f32_e32 v212, 0xbfb8aa3b, v208
	v_mul_f32_e32 v124, v124, v212
	v_mul_f32_e32 v125, v125, v212
	v_mul_f32_e32 v120, v120, v212
	v_mul_f32_e32 v121, v121, v212
	v_exp_f32_e32 v124, v124
	v_exp_f32_e32 v125, v125
	v_exp_f32_e32 v120, v120
	v_exp_f32_e32 v121, v121
	v_add_f32_e32 v124, 1.0, v124
	v_add_f32_e32 v125, 1.0, v125
	v_add_f32_e32 v208, 1.0, v120
	v_add_f32_e32 v233, 1.0, v121
	v_rcp_f32_e32 v120, v124
	v_rcp_f32_e32 v121, v125
	v_lshlrev_b32_e32 v224, 16, v206
	v_and_b32_e32 v225, 0xffff0000, v206
	v_lshlrev_b32_e32 v226, 16, v210
	v_and_b32_e32 v227, 0xffff0000, v210
	v_mul_f32_e32 v126, v126, v212
	v_mul_f32_e32 v127, v127, v212
	v_mul_f32_e32 v122, v122, v212
	v_exp_f32_e32 v126, v126
	v_exp_f32_e32 v127, v127
	v_pk_fma_f32 v[124:125], v[120:121], v[226:227], v[224:225]
	v_mul_f32_e32 v120, v123, v212
	v_exp_f32_e32 v122, v122
	v_exp_f32_e32 v123, v120
	v_mul_f32_e32 v116, v116, v212
	v_mul_f32_e32 v117, v117, v212
	v_exp_f32_e32 v116, v116
	v_exp_f32_e32 v117, v117
	v_mul_f32_e32 v118, v118, v212
	v_mul_f32_e32 v119, v119, v212
	v_add_f32_e32 v126, 1.0, v126
	v_add_f32_e32 v127, 1.0, v127
	v_exp_f32_e32 v118, v118
	v_exp_f32_e32 v119, v119
	v_mul_f32_e32 v112, v112, v212
	v_mul_f32_e32 v113, v113, v212
	v_rcp_f32_e32 v126, v126
	v_rcp_f32_e32 v127, v127
	v_add_f32_e32 v122, 1.0, v122
	v_add_f32_e32 v123, 1.0, v123
	v_exp_f32_e32 v112, v112
	v_exp_f32_e32 v113, v113
	v_rcp_f32_e32 v232, v208
	v_rcp_f32_e32 v233, v233
	v_rcp_f32_e32 v122, v122
	v_rcp_f32_e32 v123, v123
	v_add_f32_e32 v116, 1.0, v116
	v_add_f32_e32 v117, 1.0, v117
	v_lshlrev_b32_e32 v206, 16, v207
	v_and_b32_e32 v207, 0xffff0000, v207
	v_lshlrev_b32_e32 v210, 16, v211
	v_and_b32_e32 v211, 0xffff0000, v211
	v_rcp_f32_e32 v116, v116
	v_rcp_f32_e32 v117, v117
	v_add_f32_e32 v118, 1.0, v118
	v_add_f32_e32 v119, 1.0, v119
	v_pk_fma_f32 v[126:127], v[126:127], v[210:211], v[206:207]
	v_lshlrev_b32_e32 v206, 16, v209
	v_and_b32_e32 v207, 0xffff0000, v209
	v_lshlrev_b32_e32 v208, 16, v213
	v_and_b32_e32 v209, 0xffff0000, v213
	v_rcp_f32_e32 v118, v118
	v_rcp_f32_e32 v119, v119
	v_add_f32_e32 v112, 1.0, v112
	v_add_f32_e32 v113, 1.0, v113
	v_pk_fma_f32 v[120:121], v[232:233], v[230:231], v[228:229]
	v_pk_fma_f32 v[122:123], v[122:123], v[208:209], v[206:207]
	v_lshl_add_u64 v[206:207], v[222:223], 2, s[2:3]
	v_rcp_f32_e32 v112, v112
	v_rcp_f32_e32 v113, v113
	flat_store_dwordx4 v[206:207], v[120:123] offset:16
	flat_store_dwordx4 v[206:207], v[124:127]
	v_mul_f32_e32 v114, v114, v212
	v_lshlrev_b32_e32 v120, 16, v214
; __device__ __forceinline__ float bflo(unsigned u) { return __uint_as_float(u << 16); }
; __device__ __forceinline__ float bfhi(unsigned u) { return __uint_as_float(u & 0xffff0000u); }
;     __device__ __forceinline__ void operator()(const Acc& acc, const Unit& u, int wr, int wc, int fr, int fq) const {
;     ...
;             for (int m = 0; m < 4; ++m) {
;                 const int row = u.pm * 256 + ai * 128 + wr * 64 + m * 16 + fr;
;                 const float rs = rsqrtf(rsv[m] * (1.0f / DM) + EPS) * -1.4426950408889634f;
; #pragma unroll
;                 for (int bj = 0; bj < 2; ++bj) {
;                     const size_t off = (size_t)row * DM + colbase + 32 * bj;
;                     f32x4 h0 = hv[m][bj][0], h1 = hv[m][bj][1];
;                     const u32x4 p4 = pw[m][bj];
;                     const f32x4 a0 = acc[ai][bj][m][0], a1 = acc[ai][bj][m][1];
;                     h0.x += bflo(p4.x) * __builtin_amdgcn_rcpf(1.0f + __builtin_amdgcn_exp2f(a0.x * rs));
;                     h0.y += bfhi(p4.x) * __builtin_amdgcn_rcpf(1.0f + __builtin_amdgcn_exp2f(a0.y * rs));
;                     h0.z += bflo(p4.y) * __builtin_amdgcn_rcpf(1.0f + __builtin_amdgcn_exp2f(a0.z * rs));
;                     h0.w += bfhi(p4.y) * __builtin_amdgcn_rcpf(1.0f + __builtin_amdgcn_exp2f(a0.w * rs));
;                     h1.x += bflo(p4.z) * __builtin_amdgcn_rcpf(1.0f + __builtin_amdgcn_exp2f(a1.x * rs));
;                     h1.y += bfhi(p4.z) * __builtin_amdgcn_rcpf(1.0f + __builtin_amdgcn_exp2f(a1.y * rs));
;                     h1.z += bflo(p4.w) * __builtin_amdgcn_rcpf(1.0f + __builtin_amdgcn_exp2f(a1.z * rs));
;                     h1.w += bfhi(p4.w) * __builtin_amdgcn_rcpf(1.0f + __builtin_amdgcn_exp2f(a1.w * rs));
;                     *(f32x4*)(out + off) = h0; *(f32x4*)(out + off + 4) = h1;
	v_and_b32_e32 v121, 0xffff0000, v214
	v_lshlrev_b32_e32 v122, 16, v218
	v_and_b32_e32 v123, 0xffff0000, v218
	v_pk_fma_f32 v[116:117], v[116:117], v[122:123], v[120:121]
	v_lshlrev_b32_e32 v120, 16, v215
	v_and_b32_e32 v121, 0xffff0000, v215
	v_lshlrev_b32_e32 v122, 16, v219
	v_and_b32_e32 v123, 0xffff0000, v219
	v_pk_fma_f32 v[118:119], v[118:119], v[122:123], v[120:121]
	v_lshlrev_b32_e32 v120, 16, v216
	v_and_b32_e32 v121, 0xffff0000, v216
	v_lshlrev_b32_e32 v122, 16, v220
	v_and_b32_e32 v123, 0xffff0000, v220
	v_pk_fma_f32 v[112:113], v[112:113], v[122:123], v[120:121]
	v_fmamk_f32 v123, v234, 0x3a000000, v205
	v_mul_f32_e32 v124, 0x4b800000, v123
	v_cmp_gt_f32_e32 vcc, s40, v123
	flat_store_dwordx4 v[206:207], v[116:119] offset:128
	v_mul_f32_e32 v115, v115, v212
	v_cndmask_b32_e32 v123, v123, v124, vcc
	v_rsq_f32_e32 v124, v123
	v_exp_f32_e32 v114, v114
	v_exp_f32_e32 v115, v115
	v_lshlrev_b32_e32 v120, 16, v217
	v_mul_f32_e32 v116, 0x45800000, v124
	v_cndmask_b32_e32 v116, v124, v116, vcc
	v_mul_f32_e32 v116, 0xbfb8aa3b, v116
	v_mul_f32_e32 v108, v108, v116
	v_mul_f32_e32 v109, v109, v116
	v_exp_f32_e32 v108, v108
	v_exp_f32_e32 v109, v109
	v_mul_f32_e32 v110, v110, v116
	v_mul_f32_e32 v111, v111, v116
	v_exp_f32_e32 v110, v110
	v_exp_f32_e32 v111, v111
	v_mul_f32_e32 v104, v104, v116
	v_mul_f32_e32 v105, v105, v116
	v_add_f32_e32 v114, 1.0, v114
	v_add_f32_e32 v115, 1.0, v115
	v_exp_f32_e32 v104, v104
	v_exp_f32_e32 v105, v105
	v_mul_f32_e32 v106, v106, v116
	v_mul_f32_e32 v107, v107, v116
	v_rcp_f32_e32 v114, v114
	v_rcp_f32_e32 v115, v115
	v_exp_f32_e32 v106, v106
	v_exp_f32_e32 v107, v107
	v_add_f32_e32 v108, 1.0, v108
	v_add_f32_e32 v109, 1.0, v109
	v_mul_f32_e32 v100, v100, v116
	v_mul_f32_e32 v101, v101, v116
	v_rcp_f32_e32 v108, v108
	v_rcp_f32_e32 v109, v109
	v_add_f32_e32 v110, 1.0, v110
	v_add_f32_e32 v111, 1.0, v111
	v_exp_f32_e32 v100, v100
	v_exp_f32_e32 v101, v101
	v_mul_f32_e32 v102, v102, v116
	v_mul_f32_e32 v103, v103, v116
	v_and_b32_e32 v121, 0xffff0000, v217
	v_lshlrev_b32_e32 v122, 16, v221
	v_and_b32_e32 v123, 0xffff0000, v221
	v_rcp_f32_e32 v110, v110
	v_rcp_f32_e32 v111, v111
	v_add_f32_e32 v104, 1.0, v104
	v_add_f32_e32 v105, 1.0, v105
	v_exp_f32_e32 v102, v102
	v_exp_f32_e32 v103, v103
	v_mul_f32_e32 v96, v96, v116
	v_mul_f32_e32 v97, v97, v116
	v_pk_fma_f32 v[114:115], v[114:115], v[122:123], v[120:121]
	v_rcp_f32_e32 v104, v104
	v_rcp_f32_e32 v105, v105
	v_add_f32_e32 v106, 1.0, v106
	v_add_f32_e32 v107, 1.0, v107
	v_exp_f32_e32 v96, v96
	v_exp_f32_e32 v97, v97
	flat_store_dwordx4 v[206:207], v[112:115] offset:144
	v_rcp_f32_e32 v106, v106
	v_rcp_f32_e32 v107, v107
	v_lshlrev_b32_e32 v112, 16, v172
	v_and_b32_e32 v113, 0xffff0000, v172
	v_lshlrev_b32_e32 v114, 16, v168
	v_and_b32_e32 v115, 0xffff0000, v168
	v_pk_fma_f32 v[108:109], v[108:109], v[114:115], v[112:113]
	v_lshlrev_b32_e32 v112, 16, v173
	v_and_b32_e32 v113, 0xffff0000, v173
	v_lshlrev_b32_e32 v114, 16, v169
	v_and_b32_e32 v115, 0xffff0000, v169
	v_add_f32_e32 v100, 1.0, v100
	v_add_f32_e32 v101, 1.0, v101
	v_pk_fma_f32 v[110:111], v[110:111], v[114:115], v[112:113]
	v_lshlrev_b32_e32 v112, 16, v174
	v_and_b32_e32 v113, 0xffff0000, v174
	v_lshlrev_b32_e32 v114, 16, v170
	v_and_b32_e32 v115, 0xffff0000, v170
	v_rcp_f32_e32 v100, v100
	v_rcp_f32_e32 v101, v101
	v_add_f32_e32 v102, 1.0, v102
	v_add_f32_e32 v103, 1.0, v103
	v_pk_fma_f32 v[104:105], v[104:105], v[114:115], v[112:113]
	v_lshlrev_b32_e32 v112, 16, v175
	v_and_b32_e32 v113, 0xffff0000, v175
	v_lshlrev_b32_e32 v114, 16, v171
	v_and_b32_e32 v115, 0xffff0000, v171
	v_rcp_f32_e32 v102, v102
	v_rcp_f32_e32 v103, v103
	v_add_f32_e32 v96, 1.0, v96
	v_add_f32_e32 v97, 1.0, v97
	v_pk_fma_f32 v[106:107], v[106:107], v[114:115], v[112:113]
	v_lshl_add_u64 v[112:113], v[198:199], 2, s[2:3]
	v_rcp_f32_e32 v96, v96
	v_rcp_f32_e32 v97, v97
	flat_store_dwordx4 v[112:113], v[104:107] offset:16
	flat_store_dwordx4 v[112:113], v[108:111]
	v_mul_f32_e32 v98, v98, v116
	v_lshlrev_b32_e32 v104, 16, v164
	v_and_b32_e32 v105, 0xffff0000, v164
	v_lshlrev_b32_e32 v106, 16, v160
	v_and_b32_e32 v107, 0xffff0000, v160
	v_pk_fma_f32 v[100:101], v[100:101], v[106:107], v[104:105]
	v_lshlrev_b32_e32 v104, 16, v165
	v_and_b32_e32 v105, 0xffff0000, v165
	v_lshlrev_b32_e32 v106, 16, v161
	v_and_b32_e32 v107, 0xffff0000, v161
	v_pk_fma_f32 v[102:103], v[102:103], v[106:107], v[104:105]
	v_lshlrev_b32_e32 v104, 16, v166
	v_and_b32_e32 v105, 0xffff0000, v166
	v_lshlrev_b32_e32 v106, 16, v162
	v_and_b32_e32 v107, 0xffff0000, v162
	v_pk_fma_f32 v[96:97], v[96:97], v[106:107], v[104:105]
	v_fmamk_f32 v107, v235, 0x3a000000, v205
	v_mul_f32_e32 v108, 0x4b800000, v107
	v_cmp_gt_f32_e32 vcc, s40, v107
	flat_store_dwordx4 v[112:113], v[100:103] offset:128
	v_mul_f32_e32 v99, v99, v116
	v_cndmask_b32_e32 v107, v107, v108, vcc
	v_rsq_f32_e32 v108, v107
	v_exp_f32_e32 v98, v98
	v_exp_f32_e32 v99, v99
	v_lshlrev_b32_e32 v104, 16, v167
	v_mul_f32_e32 v100, 0x45800000, v108
	v_cndmask_b32_e32 v100, v108, v100, vcc
	v_mul_f32_e32 v100, 0xbfb8aa3b, v100
	v_mul_f32_e32 v92, v92, v100
	v_mul_f32_e32 v93, v93, v100
	v_exp_f32_e32 v92, v92
	v_exp_f32_e32 v93, v93
	v_mul_f32_e32 v94, v94, v100
	v_mul_f32_e32 v95, v95, v100
	v_exp_f32_e32 v94, v94
	v_exp_f32_e32 v95, v95
	v_mul_f32_e32 v88, v88, v100
	v_mul_f32_e32 v89, v89, v100
	v_add_f32_e32 v98, 1.0, v98
	v_add_f32_e32 v99, 1.0, v99
	v_exp_f32_e32 v88, v88
	v_exp_f32_e32 v89, v89
	v_mul_f32_e32 v90, v90, v100
	v_mul_f32_e32 v91, v91, v100
	v_rcp_f32_e32 v98, v98
	v_rcp_f32_e32 v99, v99
	v_exp_f32_e32 v90, v90
	v_exp_f32_e32 v91, v91
	v_add_f32_e32 v92, 1.0, v92
	v_add_f32_e32 v93, 1.0, v93
; __device__ __forceinline__ float bflo(unsigned u) { return __uint_as_float(u << 16); }
; __device__ __forceinline__ float bfhi(unsigned u) { return __uint_as_float(u & 0xffff0000u); }
;     __device__ __forceinline__ void operator()(const Acc& acc, const Unit& u, int wr, int wc, int fr, int fq) const {
;     ...
;             for (int m = 0; m < 4; ++m) {
;                 const int row = u.pm * 256 + ai * 128 + wr * 64 + m * 16 + fr;
;                 const float rs = rsqrtf(rsv[m] * (1.0f / DM) + EPS) * -1.4426950408889634f;
; #pragma unroll
;                 for (int bj = 0; bj < 2; ++bj) {
;                     const size_t off = (size_t)row * DM + colbase + 32 * bj;
;                     f32x4 h0 = hv[m][bj][0], h1 = hv[m][bj][1];
;                     const u32x4 p4 = pw[m][bj];
;                     const f32x4 a0 = acc[ai][bj][m][0], a1 = acc[ai][bj][m][1];
;                     h0.x += bflo(p4.x) * __builtin_amdgcn_rcpf(1.0f + __builtin_amdgcn_exp2f(a0.x * rs));
;                     h0.y += bfhi(p4.x) * __builtin_amdgcn_rcpf(1.0f + __builtin_amdgcn_exp2f(a0.y * rs));
;                     h0.z += bflo(p4.y) * __builtin_amdgcn_rcpf(1.0f + __builtin_amdgcn_exp2f(a0.z * rs));
;                     h0.w += bfhi(p4.y) * __builtin_amdgcn_rcpf(1.0f + __builtin_amdgcn_exp2f(a0.w * rs));
;                     h1.x += bflo(p4.z) * __builtin_amdgcn_rcpf(1.0f + __builtin_amdgcn_exp2f(a1.x * rs));
;                     h1.y += bfhi(p4.z) * __builtin_amdgcn_rcpf(1.0f + __builtin_amdgcn_exp2f(a1.y * rs));
;                     h1.z += bflo(p4.w) * __builtin_amdgcn_rcpf(1.0f + __builtin_amdgcn_exp2f(a1.z * rs));
;                     h1.w += bfhi(p4.w) * __builtin_amdgcn_rcpf(1.0f + __builtin_amdgcn_exp2f(a1.w * rs));
;                     *(f32x4*)(out + off) = h0; *(f32x4*)(out + off + 4) = h1;
	v_mul_f32_e32 v84, v84, v100
	v_mul_f32_e32 v85, v85, v100
	v_rcp_f32_e32 v92, v92
	v_rcp_f32_e32 v93, v93
	v_add_f32_e32 v94, 1.0, v94
	v_add_f32_e32 v95, 1.0, v95
	v_exp_f32_e32 v84, v84
	v_exp_f32_e32 v85, v85
	v_mul_f32_e32 v86, v86, v100
	v_mul_f32_e32 v87, v87, v100
	v_and_b32_e32 v105, 0xffff0000, v167
	v_lshlrev_b32_e32 v106, 16, v163
	v_and_b32_e32 v107, 0xffff0000, v163
	v_rcp_f32_e32 v94, v94
	v_rcp_f32_e32 v95, v95
	v_add_f32_e32 v88, 1.0, v88
	v_add_f32_e32 v89, 1.0, v89
	v_exp_f32_e32 v86, v86
	v_exp_f32_e32 v87, v87
	v_mul_f32_e32 v80, v80, v100
	v_mul_f32_e32 v81, v81, v100
	v_pk_fma_f32 v[98:99], v[98:99], v[106:107], v[104:105]
	v_rcp_f32_e32 v88, v88
	v_rcp_f32_e32 v89, v89
	v_add_f32_e32 v90, 1.0, v90
	v_add_f32_e32 v91, 1.0, v91
	v_exp_f32_e32 v80, v80
	v_exp_f32_e32 v81, v81
	flat_store_dwordx4 v[112:113], v[96:99] offset:144
	v_rcp_f32_e32 v90, v90
	v_rcp_f32_e32 v91, v91
	v_lshlrev_b32_e32 v96, 16, v156
	v_and_b32_e32 v97, 0xffff0000, v156
	v_lshlrev_b32_e32 v98, 16, v152
	v_and_b32_e32 v99, 0xffff0000, v152
	v_pk_fma_f32 v[92:93], v[92:93], v[98:99], v[96:97]
	v_lshlrev_b32_e32 v96, 16, v157
	v_and_b32_e32 v97, 0xffff0000, v157
	v_lshlrev_b32_e32 v98, 16, v153
	v_and_b32_e32 v99, 0xffff0000, v153
	v_add_f32_e32 v84, 1.0, v84
	v_add_f32_e32 v85, 1.0, v85
	v_pk_fma_f32 v[94:95], v[94:95], v[98:99], v[96:97]
	v_lshlrev_b32_e32 v96, 16, v158
	v_and_b32_e32 v97, 0xffff0000, v158
	v_lshlrev_b32_e32 v98, 16, v154
	v_and_b32_e32 v99, 0xffff0000, v154
	v_rcp_f32_e32 v84, v84
	v_rcp_f32_e32 v85, v85
	v_add_f32_e32 v86, 1.0, v86
	v_add_f32_e32 v87, 1.0, v87
	v_pk_fma_f32 v[88:89], v[88:89], v[98:99], v[96:97]
	v_lshlrev_b32_e32 v96, 16, v159
	v_and_b32_e32 v97, 0xffff0000, v159
	v_lshlrev_b32_e32 v98, 16, v155
	v_and_b32_e32 v99, 0xffff0000, v155
	v_rcp_f32_e32 v86, v86
	v_rcp_f32_e32 v87, v87
	v_add_f32_e32 v80, 1.0, v80
	v_add_f32_e32 v81, 1.0, v81
	v_pk_fma_f32 v[90:91], v[90:91], v[98:99], v[96:97]
	v_lshl_add_u64 v[96:97], v[196:197], 2, s[2:3]
	v_rcp_f32_e32 v80, v80
	v_rcp_f32_e32 v81, v81
	flat_store_dwordx4 v[96:97], v[88:91] offset:16
	flat_store_dwordx4 v[96:97], v[92:95]
	v_mul_f32_e32 v82, v82, v100
	v_lshlrev_b32_e32 v88, 16, v148
	v_and_b32_e32 v89, 0xffff0000, v148
	v_lshlrev_b32_e32 v90, 16, v144
	v_and_b32_e32 v91, 0xffff0000, v144
	v_pk_fma_f32 v[84:85], v[84:85], v[90:91], v[88:89]
	v_lshlrev_b32_e32 v88, 16, v149
	v_and_b32_e32 v89, 0xffff0000, v149
	v_lshlrev_b32_e32 v90, 16, v145
	v_and_b32_e32 v91, 0xffff0000, v145
	v_pk_fma_f32 v[86:87], v[86:87], v[90:91], v[88:89]
	v_lshlrev_b32_e32 v88, 16, v150
	v_and_b32_e32 v89, 0xffff0000, v150
	v_lshlrev_b32_e32 v90, 16, v146
	v_and_b32_e32 v91, 0xffff0000, v146
	v_pk_fma_f32 v[80:81], v[80:81], v[90:91], v[88:89]
	v_fmamk_f32 v91, v191, 0x3a000000, v205
	v_mul_f32_e32 v92, 0x4b800000, v91
	v_cmp_gt_f32_e32 vcc, s40, v91
	flat_store_dwordx4 v[96:97], v[84:87] offset:128
	v_mul_f32_e32 v83, v83, v100
	v_cndmask_b32_e32 v91, v91, v92, vcc
	v_rsq_f32_e32 v92, v91
	v_exp_f32_e32 v82, v82
	v_exp_f32_e32 v83, v83
	v_lshlrev_b32_e32 v88, 16, v151
	v_mul_f32_e32 v84, 0x45800000, v92
	v_cndmask_b32_e32 v84, v92, v84, vcc
	v_mul_f32_e32 v84, 0xbfb8aa3b, v84
	v_mul_f32_e32 v76, v76, v84
	v_mul_f32_e32 v77, v77, v84
	v_exp_f32_e32 v76, v76
	v_exp_f32_e32 v77, v77
	v_mul_f32_e32 v78, v78, v84
	v_mul_f32_e32 v79, v79, v84
	v_exp_f32_e32 v78, v78
	v_exp_f32_e32 v79, v79
	v_mul_f32_e32 v72, v72, v84
	v_mul_f32_e32 v73, v73, v84
	v_add_f32_e32 v82, 1.0, v82
	v_add_f32_e32 v83, 1.0, v83
	v_exp_f32_e32 v72, v72
	v_exp_f32_e32 v73, v73
	v_mul_f32_e32 v74, v74, v84
	v_mul_f32_e32 v75, v75, v84
	v_rcp_f32_e32 v82, v82
	v_rcp_f32_e32 v83, v83
	v_exp_f32_e32 v74, v74
	v_exp_f32_e32 v75, v75
	v_add_f32_e32 v76, 1.0, v76
	v_add_f32_e32 v77, 1.0, v77
	v_mul_f32_e32 v68, v68, v84
	v_mul_f32_e32 v69, v69, v84
	v_rcp_f32_e32 v76, v76
	v_rcp_f32_e32 v77, v77
	v_add_f32_e32 v78, 1.0, v78
	v_add_f32_e32 v79, 1.0, v79
	v_exp_f32_e32 v68, v68
	v_exp_f32_e32 v69, v69
	v_mul_f32_e32 v70, v70, v84
	v_mul_f32_e32 v71, v71, v84
	v_and_b32_e32 v89, 0xffff0000, v151
	v_lshlrev_b32_e32 v90, 16, v147
	v_and_b32_e32 v91, 0xffff0000, v147
	v_rcp_f32_e32 v78, v78
	v_rcp_f32_e32 v79, v79
	v_add_f32_e32 v72, 1.0, v72
	v_add_f32_e32 v73, 1.0, v73
	v_exp_f32_e32 v70, v70
	v_exp_f32_e32 v71, v71
	v_mul_f32_e32 v64, v64, v84
	v_mul_f32_e32 v65, v65, v84
	v_pk_fma_f32 v[82:83], v[82:83], v[90:91], v[88:89]
	v_rcp_f32_e32 v72, v72
	v_rcp_f32_e32 v73, v73
	v_add_f32_e32 v74, 1.0, v74
	v_add_f32_e32 v75, 1.0, v75
	v_exp_f32_e32 v64, v64
	v_exp_f32_e32 v65, v65
	v_mul_f32_e32 v66, v66, v84
	v_mul_f32_e32 v67, v67, v84
	flat_store_dwordx4 v[96:97], v[80:83] offset:144
	v_rcp_f32_e32 v74, v74
	v_rcp_f32_e32 v75, v75
	v_lshlrev_b32_e32 v80, 16, v140
	v_and_b32_e32 v81, 0xffff0000, v140
	v_lshlrev_b32_e32 v82, 16, v136
	v_and_b32_e32 v83, 0xffff0000, v136
	v_exp_f32_e32 v66, v66
	v_exp_f32_e32 v67, v67
	v_pk_fma_f32 v[76:77], v[76:77], v[82:83], v[80:81]
	v_lshlrev_b32_e32 v80, 16, v141
	v_and_b32_e32 v81, 0xffff0000, v141
	v_lshlrev_b32_e32 v82, 16, v137
	v_and_b32_e32 v83, 0xffff0000, v137
	v_add_f32_e32 v68, 1.0, v68
	v_add_f32_e32 v69, 1.0, v69
	v_pk_fma_f32 v[78:79], v[78:79], v[82:83], v[80:81]
	v_lshlrev_b32_e32 v80, 16, v142
	v_and_b32_e32 v81, 0xffff0000, v142
	v_lshlrev_b32_e32 v82, 16, v138
	v_and_b32_e32 v83, 0xffff0000, v138
	v_rcp_f32_e32 v68, v68
	v_rcp_f32_e32 v69, v69
	v_add_f32_e32 v70, 1.0, v70
	v_add_f32_e32 v71, 1.0, v71
	v_pk_fma_f32 v[72:73], v[72:73], v[82:83], v[80:81]
	v_lshlrev_b32_e32 v80, 16, v143
	v_and_b32_e32 v81, 0xffff0000, v143
	v_lshlrev_b32_e32 v82, 16, v139
	v_and_b32_e32 v83, 0xffff0000, v139
; __device__ __forceinline__ float bflo(unsigned u) { return __uint_as_float(u << 16); }
;     __device__ __forceinline__ void operator()(const Acc& acc, const Unit& u, int wr, int wc, int fr, int fq) const {
;     ...
;             for (int m = 0; m < 4; ++m) { const int row = u.pm * 256 + ai * 128 + wr * 64 + m * 16 + fr; const size_t off = (size_t)row * DM + colbase;
;                 rsv[m] = rowss[row];
; #pragma unroll
;                 for (int bj = 0; bj < 2; ++bj) { const u32x4 hw = __builtin_nontemporal_load((const u32x4*)(hin + off + 32 * bj));
;                     hv[m][bj][0] = (f32x4){bflo(hw.x), bfhi(hw.x), bflo(hw.y), bfhi(hw.y)}; hv[m][bj][1] = (f32x4){bflo(hw.z), bfhi(hw.z), bflo(hw.w), bfhi(hw.w)};
;                     pw[m][bj] = __builtin_nontemporal_load((const u32x4*)(PP + off + 32 * bj)); } }
; #pragma unroll
;             for (int m = 0; m < 4; ++m) {
;                 const int row = u.pm * 256 + ai * 128 + wr * 64 + m * 16 + fr;
;                 const float rs = rsqrtf(rsv[m] * (1.0f / DM) + EPS) * -1.4426950408889634f;
; #pragma unroll
;                 for (int bj = 0; bj < 2; ++bj) {
;                     const size_t off = (size_t)row * DM + colbase + 32 * bj;
;                     f32x4 h0 = hv[m][bj][0], h1 = hv[m][bj][1];
;                     const u32x4 p4 = pw[m][bj];
;                     const f32x4 a0 = acc[ai][bj][m][0], a1 = acc[ai][bj][m][1];
;                     h0.x += bflo(p4.x) * __builtin_amdgcn_rcpf(1.0f + __builtin_amdgcn_exp2f(a0.x * rs));
;                     h0.y += bfhi(p4.x) * __builtin_amdgcn_rcpf(1.0f + __builtin_amdgcn_exp2f(a0.y * rs));
;                     h0.z += bflo(p4.y) * __builtin_amdgcn_rcpf(1.0f + __builtin_amdgcn_exp2f(a0.z * rs));
;                     h0.w += bfhi(p4.y) * __builtin_amdgcn_rcpf(1.0f + __builtin_amdgcn_exp2f(a0.w * rs));
;                     h1.x += bflo(p4.z) * __builtin_amdgcn_rcpf(1.0f + __builtin_amdgcn_exp2f(a1.x * rs));
;                     h1.y += bfhi(p4.z) * __builtin_amdgcn_rcpf(1.0f + __builtin_amdgcn_exp2f(a1.y * rs));
;                     h1.z += bflo(p4.w) * __builtin_amdgcn_rcpf(1.0f + __builtin_amdgcn_exp2f(a1.z * rs));
;                     h1.w += bfhi(p4.w) * __builtin_amdgcn_rcpf(1.0f + __builtin_amdgcn_exp2f(a1.w * rs));
;                     *(f32x4*)(out + off) = h0; *(f32x4*)(out + off + 4) = h1;
	v_rcp_f32_e32 v70, v70
	v_rcp_f32_e32 v71, v71
	v_add_f32_e32 v64, 1.0, v64
	v_add_f32_e32 v65, 1.0, v65
	v_pk_fma_f32 v[74:75], v[74:75], v[82:83], v[80:81]
	v_lshl_add_u64 v[80:81], v[194:195], 2, s[2:3]
	v_rcp_f32_e32 v64, v64
	v_rcp_f32_e32 v65, v65
	v_add_f32_e32 v66, 1.0, v66
	v_add_f32_e32 v67, 1.0, v67
	flat_store_dwordx4 v[80:81], v[72:75] offset:16
	v_rcp_f32_e32 v66, v66
	v_rcp_f32_e32 v67, v67
	v_lshlrev_b32_e32 v72, 16, v132
	v_and_b32_e32 v73, 0xffff0000, v132
	v_lshlrev_b32_e32 v74, 16, v128
	v_and_b32_e32 v75, 0xffff0000, v128
	v_pk_fma_f32 v[68:69], v[68:69], v[74:75], v[72:73]
	v_lshlrev_b32_e32 v72, 16, v133
	v_and_b32_e32 v73, 0xffff0000, v133
	v_lshlrev_b32_e32 v74, 16, v129
	v_and_b32_e32 v75, 0xffff0000, v129
	v_pk_fma_f32 v[70:71], v[70:71], v[74:75], v[72:73]
	v_lshlrev_b32_e32 v72, 16, v134
	v_and_b32_e32 v73, 0xffff0000, v134
	v_lshlrev_b32_e32 v74, 16, v130
	v_and_b32_e32 v75, 0xffff0000, v130
	v_pk_fma_f32 v[64:65], v[64:65], v[74:75], v[72:73]
	v_lshlrev_b32_e32 v72, 16, v135
	v_and_b32_e32 v73, 0xffff0000, v135
	v_lshlrev_b32_e32 v74, 16, v131
	v_and_b32_e32 v75, 0xffff0000, v131
	flat_store_dwordx4 v[80:81], v[76:79]
	v_pk_fma_f32 v[66:67], v[66:67], v[74:75], v[72:73]
	flat_store_dwordx4 v[80:81], v[68:71] offset:128
	flat_store_dwordx4 v[80:81], v[64:67] offset:144
	flat_load_dword v68, v[192:193] offset:512
	s_nop 0
	v_add_u32_e32 v64, 0x80, v190
	v_ashrrev_i32_e32 v65, 31, v64
	v_lshlrev_b64 v[64:65], 11, v[64:65]
	v_lshl_add_u64 v[136:137], v[64:65], 0, v[188:189]
	v_lshlrev_b64 v[64:65], 1, v[136:137]
	v_lshl_add_u64 v[66:67], s[6:7], 0, v[64:65]
	v_lshl_add_u64 v[64:65], s[8:9], 0, v[64:65]
	flat_load_dwordx4 v[124:127], v[66:67] nt
	flat_load_dwordx4 v[128:131], v[64:65] nt
	flat_load_dwordx4 v[132:135], v[66:67] offset:64 nt
	flat_load_dwordx4 v[112:115], v[64:65] offset:64 nt
	v_add_u32_e32 v64, 0x90, v190
	v_ashrrev_i32_e32 v65, 31, v64
	v_lshlrev_b64 v[64:65], 11, v[64:65]
	v_lshl_add_u64 v[120:121], v[64:65], 0, v[188:189]
	v_lshlrev_b64 v[64:65], 1, v[120:121]
	v_lshl_add_u64 v[66:67], s[6:7], 0, v[64:65]
	v_lshl_add_u64 v[64:65], s[8:9], 0, v[64:65]
	flat_load_dwordx4 v[108:111], v[66:67] nt
	flat_load_dwordx4 v[100:103], v[66:67] offset:64 nt
	flat_load_dwordx4 v[104:107], v[64:65] nt
	flat_load_dwordx4 v[96:99], v[64:65] offset:64 nt
	v_add_u32_e32 v64, 0xa0, v190
	v_ashrrev_i32_e32 v65, 31, v64
	v_lshlrev_b64 v[64:65], 11, v[64:65]
	v_lshl_add_u64 v[118:119], v[64:65], 0, v[188:189]
	v_lshlrev_b64 v[64:65], 1, v[118:119]
	v_lshl_add_u64 v[66:67], s[6:7], 0, v[64:65]
	v_lshl_add_u64 v[64:65], s[8:9], 0, v[64:65]
	flat_load_dwordx4 v[92:95], v[66:67] nt
	flat_load_dwordx4 v[84:87], v[66:67] offset:64 nt
	flat_load_dwordx4 v[88:91], v[64:65] nt
	flat_load_dwordx4 v[80:83], v[64:65] offset:64 nt
	flat_load_dword v123, v[192:193] offset:576
	flat_load_dword v142, v[192:193] offset:640
	flat_load_dword v122, v[192:193] offset:704
	v_add_u32_e32 v64, 0xb0, v190
	v_ashrrev_i32_e32 v65, 31, v64
	v_lshlrev_b64 v[64:65], 11, v[64:65]
	v_lshl_add_u64 v[116:117], v[64:65], 0, v[188:189]
	v_lshlrev_b64 v[64:65], 1, v[116:117]
	v_lshl_add_u64 v[66:67], s[6:7], 0, v[64:65]
	s_waitcnt vmcnt(0) lgkmcnt(0)
	v_fmamk_f32 v68, v68, 0x3a000000, v205
	v_mul_f32_e32 v69, 0x4b800000, v68
	v_cmp_gt_f32_e32 vcc, s40, v68
	v_lshlrev_b32_e32 v140, 16, v128
	s_nop 0
	v_cndmask_b32_e32 v68, v68, v69, vcc
	v_rsq_f32_e32 v70, v68
	v_lshl_add_u64 v[68:69], s[8:9], 0, v[64:65]
	v_lshlrev_b32_e32 v138, 16, v124
	v_and_b32_e32 v139, 0xffff0000, v124
	v_mul_f32_e32 v71, 0x45800000, v70
	v_cndmask_b32_e32 v70, v70, v71, vcc
	v_mul_f32_e32 v143, 0xbfb8aa3b, v70
	v_mul_f32_e32 v62, v62, v143
	v_mul_f32_e32 v63, v63, v143
	v_exp_f32_e32 v62, v62
	v_exp_f32_e32 v63, v63
	v_mul_f32_e32 v56, v56, v143
	v_mul_f32_e32 v57, v57, v143
	v_exp_f32_e32 v56, v56
	v_exp_f32_e32 v57, v57
	v_mul_f32_e32 v58, v58, v143
	v_mul_f32_e32 v59, v59, v143
	v_exp_f32_e32 v58, v58
	v_exp_f32_e32 v59, v59
	v_mul_f32_e32 v52, v52, v143
	v_mul_f32_e32 v53, v53, v143
	v_add_f32_e32 v62, 1.0, v62
	v_add_f32_e32 v63, 1.0, v63
	v_exp_f32_e32 v52, v52
	v_exp_f32_e32 v53, v53
	v_mul_f32_e32 v54, v54, v143
	v_mul_f32_e32 v55, v55, v143
	v_mul_f32_e32 v60, v60, v143
	v_mul_f32_e32 v61, v61, v143
	v_rcp_f32_e32 v62, v62
	v_rcp_f32_e32 v63, v63
	v_add_f32_e32 v56, 1.0, v56
	v_add_f32_e32 v57, 1.0, v57
	v_exp_f32_e32 v54, v54
	v_exp_f32_e32 v55, v55
	v_mul_f32_e32 v48, v48, v143
	v_mul_f32_e32 v49, v49, v143
	v_exp_f32_e32 v60, v60
	v_exp_f32_e32 v61, v61
	v_rcp_f32_e32 v56, v56
	v_rcp_f32_e32 v57, v57
	v_add_f32_e32 v58, 1.0, v58
	v_add_f32_e32 v59, 1.0, v59
	v_exp_f32_e32 v48, v48
	v_exp_f32_e32 v49, v49
	v_rcp_f32_e32 v58, v58
	v_rcp_f32_e32 v59, v59
	v_and_b32_e32 v141, 0xffff0000, v128
	v_lshlrev_b32_e32 v124, 16, v125
	v_and_b32_e32 v125, 0xffff0000, v125
	v_lshlrev_b32_e32 v128, 16, v129
	v_and_b32_e32 v129, 0xffff0000, v129
	v_add_f32_e32 v52, 1.0, v52
	v_add_f32_e32 v53, 1.0, v53
	flat_load_dwordx4 v[72:75], v[66:67] nt
	s_nop 0
	flat_load_dwordx4 v[64:67], v[66:67] offset:64 nt
	s_nop 0
	flat_load_dwordx4 v[76:79], v[68:69] nt
	s_nop 0
	flat_load_dwordx4 v[68:71], v[68:69] offset:64 nt
	v_pk_fma_f32 v[62:63], v[62:63], v[128:129], v[124:125]
	v_lshlrev_b32_e32 v124, 16, v126
	v_and_b32_e32 v125, 0xffff0000, v126
	v_lshlrev_b32_e32 v128, 16, v130
	v_and_b32_e32 v129, 0xffff0000, v130
	v_rcp_f32_e32 v52, v52
	v_rcp_f32_e32 v53, v53
	v_add_f32_e32 v54, 1.0, v54
	v_add_f32_e32 v55, 1.0, v55
	v_add_f32_e32 v60, 1.0, v60
	v_add_f32_e32 v61, 1.0, v61
	v_pk_fma_f32 v[56:57], v[56:57], v[128:129], v[124:125]
	v_lshlrev_b32_e32 v124, 16, v127
	v_and_b32_e32 v125, 0xffff0000, v127
; __device__ __forceinline__ float bflo(unsigned u) { return __uint_as_float(u << 16); }
; __device__ __forceinline__ float bfhi(unsigned u) { return __uint_as_float(u & 0xffff0000u); }
;     __device__ __forceinline__ void operator()(const Acc& acc, const Unit& u, int wr, int wc, int fr, int fq) const {
;     ...
;             for (int m = 0; m < 4; ++m) {
;                 const int row = u.pm * 256 + ai * 128 + wr * 64 + m * 16 + fr;
;                 const float rs = rsqrtf(rsv[m] * (1.0f / DM) + EPS) * -1.4426950408889634f;
; #pragma unroll
;                 for (int bj = 0; bj < 2; ++bj) {
;                     const size_t off = (size_t)row * DM + colbase + 32 * bj;
;                     f32x4 h0 = hv[m][bj][0], h1 = hv[m][bj][1];
;                     const u32x4 p4 = pw[m][bj];
;                     const f32x4 a0 = acc[ai][bj][m][0], a1 = acc[ai][bj][m][1];
;                     h0.x += bflo(p4.x) * __builtin_amdgcn_rcpf(1.0f + __builtin_amdgcn_exp2f(a0.x * rs));
;                     h0.y += bfhi(p4.x) * __builtin_amdgcn_rcpf(1.0f + __builtin_amdgcn_exp2f(a0.y * rs));
;                     h0.z += bflo(p4.y) * __builtin_amdgcn_rcpf(1.0f + __builtin_amdgcn_exp2f(a0.z * rs));
;                     h0.w += bfhi(p4.y) * __builtin_amdgcn_rcpf(1.0f + __builtin_amdgcn_exp2f(a0.w * rs));
;                     h1.x += bflo(p4.z) * __builtin_amdgcn_rcpf(1.0f + __builtin_amdgcn_exp2f(a1.x * rs));
;                     h1.y += bfhi(p4.z) * __builtin_amdgcn_rcpf(1.0f + __builtin_amdgcn_exp2f(a1.y * rs));
;                     h1.z += bflo(p4.w) * __builtin_amdgcn_rcpf(1.0f + __builtin_amdgcn_exp2f(a1.z * rs));
;                     h1.w += bfhi(p4.w) * __builtin_amdgcn_rcpf(1.0f + __builtin_amdgcn_exp2f(a1.w * rs));
;                     *(f32x4*)(out + off) = h0; *(f32x4*)(out + off + 4) = h1;
	v_lshlrev_b32_e32 v126, 16, v131
	v_and_b32_e32 v127, 0xffff0000, v131
	v_rcp_f32_e32 v54, v54
	v_rcp_f32_e32 v55, v55
	v_add_f32_e32 v48, 1.0, v48
	v_add_f32_e32 v49, 1.0, v49
	v_rcp_f32_e32 v60, v60
	v_rcp_f32_e32 v61, v61
	v_pk_fma_f32 v[58:59], v[58:59], v[126:127], v[124:125]
	v_lshl_add_u64 v[124:125], v[136:137], 2, s[2:3]
	v_rcp_f32_e32 v48, v48
	v_rcp_f32_e32 v49, v49
	flat_store_dwordx4 v[124:125], v[56:59] offset:16
	v_pk_fma_f32 v[60:61], v[60:61], v[140:141], v[138:139]
	flat_store_dwordx4 v[124:125], v[60:63]
	v_lshlrev_b32_e32 v56, 16, v132
	v_and_b32_e32 v57, 0xffff0000, v132
	v_lshlrev_b32_e32 v58, 16, v112
	v_and_b32_e32 v59, 0xffff0000, v112
	v_pk_fma_f32 v[52:53], v[52:53], v[58:59], v[56:57]
	v_lshlrev_b32_e32 v56, 16, v133
	v_and_b32_e32 v57, 0xffff0000, v133
	v_lshlrev_b32_e32 v58, 16, v113
	v_and_b32_e32 v59, 0xffff0000, v113
	v_pk_fma_f32 v[54:55], v[54:55], v[58:59], v[56:57]
	v_lshlrev_b32_e32 v56, 16, v134
	v_and_b32_e32 v57, 0xffff0000, v134
	v_lshlrev_b32_e32 v58, 16, v114
	v_and_b32_e32 v59, 0xffff0000, v114
	v_pk_fma_f32 v[48:49], v[48:49], v[58:59], v[56:57]
	v_fmamk_f32 v59, v123, 0x3a000000, v205
	v_mul_f32_e32 v60, 0x4b800000, v59
	v_cmp_gt_f32_e32 vcc, s40, v59
	flat_store_dwordx4 v[124:125], v[52:55] offset:128
	v_mul_f32_e32 v50, v50, v143
	v_cndmask_b32_e32 v59, v59, v60, vcc
	v_rsq_f32_e32 v60, v59
	v_mul_f32_e32 v51, v51, v143
	v_exp_f32_e32 v50, v50
	v_exp_f32_e32 v51, v51
	v_mul_f32_e32 v52, 0x45800000, v60
	v_cndmask_b32_e32 v52, v60, v52, vcc
	v_mul_f32_e32 v52, 0xbfb8aa3b, v52
	v_mul_f32_e32 v44, v44, v52
	v_mul_f32_e32 v45, v45, v52
	v_exp_f32_e32 v44, v44
	v_exp_f32_e32 v45, v45
	v_mul_f32_e32 v46, v46, v52
	v_mul_f32_e32 v47, v47, v52
	v_exp_f32_e32 v46, v46
	v_exp_f32_e32 v47, v47
	v_mul_f32_e32 v40, v40, v52
	v_mul_f32_e32 v41, v41, v52
	v_add_f32_e32 v50, 1.0, v50
	v_add_f32_e32 v51, 1.0, v51
	v_exp_f32_e32 v40, v40
	v_exp_f32_e32 v41, v41
	v_mul_f32_e32 v42, v42, v52
	v_mul_f32_e32 v43, v43, v52
	v_rcp_f32_e32 v50, v50
	v_rcp_f32_e32 v51, v51
	v_exp_f32_e32 v42, v42
	v_exp_f32_e32 v43, v43
	v_add_f32_e32 v44, 1.0, v44
	v_add_f32_e32 v45, 1.0, v45
	v_mul_f32_e32 v36, v36, v52
	v_mul_f32_e32 v37, v37, v52
	v_rcp_f32_e32 v44, v44
	v_rcp_f32_e32 v45, v45
	v_add_f32_e32 v46, 1.0, v46
	v_add_f32_e32 v47, 1.0, v47
	v_exp_f32_e32 v36, v36
	v_exp_f32_e32 v37, v37
	v_mul_f32_e32 v38, v38, v52
	v_mul_f32_e32 v39, v39, v52
	v_lshlrev_b32_e32 v56, 16, v135
	v_and_b32_e32 v57, 0xffff0000, v135
	v_lshlrev_b32_e32 v58, 16, v115
	v_and_b32_e32 v59, 0xffff0000, v115
	v_rcp_f32_e32 v46, v46
	v_rcp_f32_e32 v47, v47
	v_add_f32_e32 v40, 1.0, v40
	v_add_f32_e32 v41, 1.0, v41
	v_exp_f32_e32 v38, v38
	v_exp_f32_e32 v39, v39
	v_mul_f32_e32 v32, v32, v52
	v_mul_f32_e32 v33, v33, v52
	v_pk_fma_f32 v[50:51], v[50:51], v[58:59], v[56:57]
	v_rcp_f32_e32 v40, v40
	v_rcp_f32_e32 v41, v41
	v_add_f32_e32 v42, 1.0, v42
	v_add_f32_e32 v43, 1.0, v43
	v_exp_f32_e32 v32, v32
	v_exp_f32_e32 v33, v33
	flat_store_dwordx4 v[124:125], v[48:51] offset:144
	v_rcp_f32_e32 v42, v42
	v_rcp_f32_e32 v43, v43
	v_lshlrev_b32_e32 v48, 16, v108
	v_and_b32_e32 v49, 0xffff0000, v108
	v_lshlrev_b32_e32 v50, 16, v104
	v_and_b32_e32 v51, 0xffff0000, v104
	v_pk_fma_f32 v[44:45], v[44:45], v[50:51], v[48:49]
	v_lshlrev_b32_e32 v48, 16, v109
	v_and_b32_e32 v49, 0xffff0000, v109
	v_lshlrev_b32_e32 v50, 16, v105
	v_and_b32_e32 v51, 0xffff0000, v105
	v_add_f32_e32 v36, 1.0, v36
	v_add_f32_e32 v37, 1.0, v37
	v_pk_fma_f32 v[46:47], v[46:47], v[50:51], v[48:49]
	v_lshlrev_b32_e32 v48, 16, v110
	v_and_b32_e32 v49, 0xffff0000, v110
	v_lshlrev_b32_e32 v50, 16, v106
	v_and_b32_e32 v51, 0xffff0000, v106
	v_rcp_f32_e32 v36, v36
	v_rcp_f32_e32 v37, v37
	v_add_f32_e32 v38, 1.0, v38
	v_add_f32_e32 v39, 1.0, v39
	v_pk_fma_f32 v[40:41], v[40:41], v[50:51], v[48:49]
	v_lshlrev_b32_e32 v48, 16, v111
	v_and_b32_e32 v49, 0xffff0000, v111
	v_lshlrev_b32_e32 v50, 16, v107
	v_and_b32_e32 v51, 0xffff0000, v107
	v_rcp_f32_e32 v38, v38
	v_rcp_f32_e32 v39, v39
	v_add_f32_e32 v32, 1.0, v32
	v_add_f32_e32 v33, 1.0, v33
	v_pk_fma_f32 v[42:43], v[42:43], v[50:51], v[48:49]
	v_lshl_add_u64 v[48:49], v[120:121], 2, s[2:3]
	v_rcp_f32_e32 v32, v32
	v_rcp_f32_e32 v33, v33
	flat_store_dwordx4 v[48:49], v[40:43] offset:16
	flat_store_dwordx4 v[48:49], v[44:47]
	v_mul_f32_e32 v34, v34, v52
	v_lshlrev_b32_e32 v40, 16, v100
	v_and_b32_e32 v41, 0xffff0000, v100
	v_lshlrev_b32_e32 v42, 16, v96
	v_and_b32_e32 v43, 0xffff0000, v96
	v_pk_fma_f32 v[36:37], v[36:37], v[42:43], v[40:41]
	v_lshlrev_b32_e32 v40, 16, v101
	v_and_b32_e32 v41, 0xffff0000, v101
	v_lshlrev_b32_e32 v42, 16, v97
	v_and_b32_e32 v43, 0xffff0000, v97
	v_pk_fma_f32 v[38:39], v[38:39], v[42:43], v[40:41]
	v_lshlrev_b32_e32 v40, 16, v102
	v_and_b32_e32 v41, 0xffff0000, v102
	v_lshlrev_b32_e32 v42, 16, v98
	v_and_b32_e32 v43, 0xffff0000, v98
	v_pk_fma_f32 v[32:33], v[32:33], v[42:43], v[40:41]
	v_fmamk_f32 v43, v142, 0x3a000000, v205
	v_mul_f32_e32 v44, 0x4b800000, v43
	v_cmp_gt_f32_e32 vcc, s40, v43
	flat_store_dwordx4 v[48:49], v[36:39] offset:128
	v_mul_f32_e32 v35, v35, v52
	v_cndmask_b32_e32 v43, v43, v44, vcc
	v_rsq_f32_e32 v44, v43
	v_exp_f32_e32 v34, v34
	v_exp_f32_e32 v35, v35
	v_lshlrev_b32_e32 v40, 16, v103
	v_mul_f32_e32 v36, 0x45800000, v44
	v_cndmask_b32_e32 v36, v44, v36, vcc
	v_mul_f32_e32 v36, 0xbfb8aa3b, v36
	v_mul_f32_e32 v28, v28, v36
	v_mul_f32_e32 v29, v29, v36
	v_exp_f32_e32 v28, v28
	v_exp_f32_e32 v29, v29
	v_mul_f32_e32 v30, v30, v36
	v_mul_f32_e32 v31, v31, v36
	v_exp_f32_e32 v30, v30
	v_exp_f32_e32 v31, v31
	v_mul_f32_e32 v24, v24, v36
	v_mul_f32_e32 v25, v25, v36
	v_add_f32_e32 v34, 1.0, v34
; __device__ __forceinline__ float bflo(unsigned u) { return __uint_as_float(u << 16); }
; __device__ __forceinline__ float bfhi(unsigned u) { return __uint_as_float(u & 0xffff0000u); }
;     __device__ __forceinline__ void operator()(const Acc& acc, const Unit& u, int wr, int wc, int fr, int fq) const {
;     ...
;             for (int m = 0; m < 4; ++m) {
;                 const int row = u.pm * 256 + ai * 128 + wr * 64 + m * 16 + fr;
;                 const float rs = rsqrtf(rsv[m] * (1.0f / DM) + EPS) * -1.4426950408889634f;
; #pragma unroll
;                 for (int bj = 0; bj < 2; ++bj) {
;                     const size_t off = (size_t)row * DM + colbase + 32 * bj;
;                     f32x4 h0 = hv[m][bj][0], h1 = hv[m][bj][1];
;                     const u32x4 p4 = pw[m][bj];
;                     const f32x4 a0 = acc[ai][bj][m][0], a1 = acc[ai][bj][m][1];
;                     h0.x += bflo(p4.x) * __builtin_amdgcn_rcpf(1.0f + __builtin_amdgcn_exp2f(a0.x * rs));
;                     h0.y += bfhi(p4.x) * __builtin_amdgcn_rcpf(1.0f + __builtin_amdgcn_exp2f(a0.y * rs));
;                     h0.z += bflo(p4.y) * __builtin_amdgcn_rcpf(1.0f + __builtin_amdgcn_exp2f(a0.z * rs));
;                     h0.w += bfhi(p4.y) * __builtin_amdgcn_rcpf(1.0f + __builtin_amdgcn_exp2f(a0.w * rs));
;                     h1.x += bflo(p4.z) * __builtin_amdgcn_rcpf(1.0f + __builtin_amdgcn_exp2f(a1.x * rs));
;                     h1.y += bfhi(p4.z) * __builtin_amdgcn_rcpf(1.0f + __builtin_amdgcn_exp2f(a1.y * rs));
;                     h1.z += bflo(p4.w) * __builtin_amdgcn_rcpf(1.0f + __builtin_amdgcn_exp2f(a1.z * rs));
;                     h1.w += bfhi(p4.w) * __builtin_amdgcn_rcpf(1.0f + __builtin_amdgcn_exp2f(a1.w * rs));
;                     *(f32x4*)(out + off) = h0; *(f32x4*)(out + off + 4) = h1;
	v_add_f32_e32 v35, 1.0, v35
	v_exp_f32_e32 v24, v24
	v_exp_f32_e32 v25, v25
	v_mul_f32_e32 v26, v26, v36
	v_mul_f32_e32 v27, v27, v36
	v_rcp_f32_e32 v34, v34
	v_rcp_f32_e32 v35, v35
	v_exp_f32_e32 v26, v26
	v_exp_f32_e32 v27, v27
	v_add_f32_e32 v28, 1.0, v28
	v_add_f32_e32 v29, 1.0, v29
	v_mul_f32_e32 v20, v20, v36
	v_mul_f32_e32 v21, v21, v36
	v_rcp_f32_e32 v28, v28
	v_rcp_f32_e32 v29, v29
	v_add_f32_e32 v30, 1.0, v30
	v_add_f32_e32 v31, 1.0, v31
	v_exp_f32_e32 v20, v20
	v_exp_f32_e32 v21, v21
	v_mul_f32_e32 v22, v22, v36
	v_mul_f32_e32 v23, v23, v36
	v_and_b32_e32 v41, 0xffff0000, v103
	v_lshlrev_b32_e32 v42, 16, v99
	v_and_b32_e32 v43, 0xffff0000, v99
	v_rcp_f32_e32 v30, v30
	v_rcp_f32_e32 v31, v31
	v_add_f32_e32 v24, 1.0, v24
	v_add_f32_e32 v25, 1.0, v25
	v_exp_f32_e32 v22, v22
	v_exp_f32_e32 v23, v23
	v_mul_f32_e32 v16, v16, v36
	v_mul_f32_e32 v17, v17, v36
	v_pk_fma_f32 v[34:35], v[34:35], v[42:43], v[40:41]
	v_rcp_f32_e32 v24, v24
	v_rcp_f32_e32 v25, v25
	v_add_f32_e32 v26, 1.0, v26
	v_add_f32_e32 v27, 1.0, v27
	v_exp_f32_e32 v16, v16
	v_exp_f32_e32 v17, v17
	flat_store_dwordx4 v[48:49], v[32:35] offset:144
	v_rcp_f32_e32 v26, v26
	v_rcp_f32_e32 v27, v27
	v_lshlrev_b32_e32 v32, 16, v92
	v_and_b32_e32 v33, 0xffff0000, v92
	v_lshlrev_b32_e32 v34, 16, v88
	v_and_b32_e32 v35, 0xffff0000, v88
	v_pk_fma_f32 v[28:29], v[28:29], v[34:35], v[32:33]
	v_lshlrev_b32_e32 v32, 16, v93
	v_and_b32_e32 v33, 0xffff0000, v93
	v_lshlrev_b32_e32 v34, 16, v89
	v_and_b32_e32 v35, 0xffff0000, v89
	v_add_f32_e32 v20, 1.0, v20
	v_add_f32_e32 v21, 1.0, v21
	v_pk_fma_f32 v[30:31], v[30:31], v[34:35], v[32:33]
	v_lshlrev_b32_e32 v32, 16, v94
	v_and_b32_e32 v33, 0xffff0000, v94
	v_lshlrev_b32_e32 v34, 16, v90
	v_and_b32_e32 v35, 0xffff0000, v90
	v_rcp_f32_e32 v20, v20
	v_rcp_f32_e32 v21, v21
	v_add_f32_e32 v22, 1.0, v22
	v_add_f32_e32 v23, 1.0, v23
	v_pk_fma_f32 v[24:25], v[24:25], v[34:35], v[32:33]
	v_lshlrev_b32_e32 v32, 16, v95
	v_and_b32_e32 v33, 0xffff0000, v95
	v_lshlrev_b32_e32 v34, 16, v91
	v_and_b32_e32 v35, 0xffff0000, v91
	v_rcp_f32_e32 v22, v22
	v_rcp_f32_e32 v23, v23
	v_add_f32_e32 v16, 1.0, v16
	v_add_f32_e32 v17, 1.0, v17
	v_pk_fma_f32 v[26:27], v[26:27], v[34:35], v[32:33]
	v_lshl_add_u64 v[32:33], v[118:119], 2, s[2:3]
	v_rcp_f32_e32 v16, v16
	v_rcp_f32_e32 v17, v17
	flat_store_dwordx4 v[32:33], v[24:27] offset:16
	flat_store_dwordx4 v[32:33], v[28:31]
	v_mul_f32_e32 v18, v18, v36
	v_lshlrev_b32_e32 v24, 16, v84
	v_and_b32_e32 v25, 0xffff0000, v84
	v_lshlrev_b32_e32 v26, 16, v80
	v_and_b32_e32 v27, 0xffff0000, v80
	v_pk_fma_f32 v[20:21], v[20:21], v[26:27], v[24:25]
	v_lshlrev_b32_e32 v24, 16, v85
	v_and_b32_e32 v25, 0xffff0000, v85
	v_lshlrev_b32_e32 v26, 16, v81
	v_and_b32_e32 v27, 0xffff0000, v81
	v_pk_fma_f32 v[22:23], v[22:23], v[26:27], v[24:25]
	v_lshlrev_b32_e32 v24, 16, v86
	v_and_b32_e32 v25, 0xffff0000, v86
	v_lshlrev_b32_e32 v26, 16, v82
	v_and_b32_e32 v27, 0xffff0000, v82
	v_pk_fma_f32 v[16:17], v[16:17], v[26:27], v[24:25]
	v_fmamk_f32 v27, v122, 0x3a000000, v205
	v_mul_f32_e32 v28, 0x4b800000, v27
	v_cmp_gt_f32_e32 vcc, s40, v27
	flat_store_dwordx4 v[32:33], v[20:23] offset:128
	v_mul_f32_e32 v19, v19, v36
	v_cndmask_b32_e32 v27, v27, v28, vcc
	v_rsq_f32_e32 v28, v27
	v_exp_f32_e32 v18, v18
	v_exp_f32_e32 v19, v19
	v_lshlrev_b32_e32 v24, 16, v87
	v_mul_f32_e32 v20, 0x45800000, v28
	v_cndmask_b32_e32 v20, v28, v20, vcc
	v_mul_f32_e32 v20, 0xbfb8aa3b, v20
	v_mul_f32_e32 v12, v12, v20
	v_mul_f32_e32 v13, v13, v20
	v_exp_f32_e32 v12, v12
	v_exp_f32_e32 v13, v13
	v_mul_f32_e32 v14, v14, v20
	v_mul_f32_e32 v15, v15, v20
	v_exp_f32_e32 v14, v14
	v_exp_f32_e32 v15, v15
	v_mul_f32_e32 v8, v8, v20
	v_mul_f32_e32 v9, v9, v20
	v_add_f32_e32 v18, 1.0, v18
	v_add_f32_e32 v19, 1.0, v19
	v_exp_f32_e32 v8, v8
	v_exp_f32_e32 v9, v9
	v_mul_f32_e32 v10, v10, v20
	v_mul_f32_e32 v11, v11, v20
	v_rcp_f32_e32 v18, v18
	v_rcp_f32_e32 v19, v19
	v_exp_f32_e32 v10, v10
	v_exp_f32_e32 v11, v11
	v_add_f32_e32 v12, 1.0, v12
	v_add_f32_e32 v13, 1.0, v13
	v_mul_f32_e32 v4, v4, v20
	v_mul_f32_e32 v5, v5, v20
	v_rcp_f32_e32 v12, v12
	v_rcp_f32_e32 v13, v13
	v_add_f32_e32 v14, 1.0, v14
	v_add_f32_e32 v15, 1.0, v15
	v_exp_f32_e32 v4, v4
	v_exp_f32_e32 v5, v5
	v_mul_f32_e32 v6, v6, v20
	v_mul_f32_e32 v7, v7, v20
	v_and_b32_e32 v25, 0xffff0000, v87
	v_lshlrev_b32_e32 v26, 16, v83
	v_and_b32_e32 v27, 0xffff0000, v83
	v_rcp_f32_e32 v14, v14
	v_rcp_f32_e32 v15, v15
	v_add_f32_e32 v8, 1.0, v8
	v_add_f32_e32 v9, 1.0, v9
	v_exp_f32_e32 v6, v6
	v_exp_f32_e32 v7, v7
	v_mul_f32_e32 v0, v0, v20
	v_mul_f32_e32 v1, v1, v20
	v_pk_fma_f32 v[18:19], v[18:19], v[26:27], v[24:25]
	v_rcp_f32_e32 v8, v8
	v_rcp_f32_e32 v9, v9
	v_add_f32_e32 v10, 1.0, v10
	v_add_f32_e32 v11, 1.0, v11
	v_exp_f32_e32 v0, v0
	v_exp_f32_e32 v1, v1
	v_mul_f32_e32 v2, v2, v20
	v_mul_f32_e32 v3, v3, v20
	flat_store_dwordx4 v[32:33], v[16:19] offset:144
	v_rcp_f32_e32 v10, v10
	v_rcp_f32_e32 v11, v11
	s_waitcnt vmcnt(0) lgkmcnt(0)
; __device__ __forceinline__ float bflo(unsigned u) { return __uint_as_float(u << 16); }
; __device__ __forceinline__ float bfhi(unsigned u) { return __uint_as_float(u & 0xffff0000u); }
; #define PG8_BAR __builtin_amdgcn_s_barrier()
; template <class Epi, bool ALIGN_EPI>
; __device__ __forceinline__ void gemm_phase(LAS unsigned char* lds, const Gemm g, const StaticOrder& S, const Epi& E, const int wid) {
;     ...
;         if (!has_next) break;
; #pragma unroll
;         for (int a = 0; a < 2; ++a)
; #pragma unroll
;             for (int b = 0; b < 2; ++b)
; #pragma unroll
;                 for (int m = 0; m < 4; ++m)
; #pragma unroll
;                     for (int n = 0; n < 2; ++n) acc[a][b][m][n] = (f32x4){0.f, 0.f, 0.f, 0.f};
;         cur = nxt; cA = nA; cB = nB; ++ui;
;         if constexpr (ALIGN_EPI) { if (wr == 1) PG8_BAR; }
;     __device__ __forceinline__ void operator()(const Acc& acc, const Unit& u, int wr, int wc, int fr, int fq) const {
;     ...
;                     h0.x += bflo(p4.x) * __builtin_amdgcn_rcpf(1.0f + __builtin_amdgcn_exp2f(a0.x * rs));
;                     h0.y += bfhi(p4.x) * __builtin_amdgcn_rcpf(1.0f + __builtin_amdgcn_exp2f(a0.y * rs));
;                     h0.z += bflo(p4.y) * __builtin_amdgcn_rcpf(1.0f + __builtin_amdgcn_exp2f(a0.z * rs));
;                     h0.w += bfhi(p4.y) * __builtin_amdgcn_rcpf(1.0f + __builtin_amdgcn_exp2f(a0.w * rs));
;                     h1.x += bflo(p4.z) * __builtin_amdgcn_rcpf(1.0f + __builtin_amdgcn_exp2f(a1.x * rs));
;                     h1.y += bfhi(p4.z) * __builtin_amdgcn_rcpf(1.0f + __builtin_amdgcn_exp2f(a1.y * rs));
;                     h1.z += bflo(p4.w) * __builtin_amdgcn_rcpf(1.0f + __builtin_amdgcn_exp2f(a1.z * rs));
;                     h1.w += bfhi(p4.w) * __builtin_amdgcn_rcpf(1.0f + __builtin_amdgcn_exp2f(a1.w * rs));
;                     *(f32x4*)(out + off) = h0; *(f32x4*)(out + off + 4) = h1;
	v_lshlrev_b32_e32 v16, 16, v72
	v_and_b32_e32 v17, 0xffff0000, v72
	v_lshlrev_b32_e32 v18, 16, v76
	v_and_b32_e32 v19, 0xffff0000, v76
	v_exp_f32_e32 v2, v2
	v_exp_f32_e32 v3, v3
	v_pk_fma_f32 v[12:13], v[12:13], v[18:19], v[16:17]
	v_lshlrev_b32_e32 v16, 16, v73
	v_and_b32_e32 v17, 0xffff0000, v73
	v_lshlrev_b32_e32 v18, 16, v77
	v_and_b32_e32 v19, 0xffff0000, v77
	v_add_f32_e32 v4, 1.0, v4
	v_add_f32_e32 v5, 1.0, v5
	v_pk_fma_f32 v[14:15], v[14:15], v[18:19], v[16:17]
	v_lshlrev_b32_e32 v16, 16, v74
	v_and_b32_e32 v17, 0xffff0000, v74
	v_lshlrev_b32_e32 v18, 16, v78
	v_and_b32_e32 v19, 0xffff0000, v78
	v_rcp_f32_e32 v4, v4
	v_rcp_f32_e32 v5, v5
	v_add_f32_e32 v6, 1.0, v6
	v_add_f32_e32 v7, 1.0, v7
	v_pk_fma_f32 v[8:9], v[8:9], v[18:19], v[16:17]
	v_lshlrev_b32_e32 v16, 16, v75
	v_and_b32_e32 v17, 0xffff0000, v75
	v_lshlrev_b32_e32 v18, 16, v79
	v_and_b32_e32 v19, 0xffff0000, v79
	v_rcp_f32_e32 v6, v6
	v_rcp_f32_e32 v7, v7
	v_add_f32_e32 v0, 1.0, v0
	v_add_f32_e32 v1, 1.0, v1
	v_pk_fma_f32 v[10:11], v[10:11], v[18:19], v[16:17]
	v_lshl_add_u64 v[16:17], v[116:117], 2, s[2:3]
	v_rcp_f32_e32 v0, v0
	v_rcp_f32_e32 v1, v1
	v_add_f32_e32 v2, 1.0, v2
	v_add_f32_e32 v3, 1.0, v3
	flat_store_dwordx4 v[16:17], v[8:11] offset:16
	v_rcp_f32_e32 v2, v2
	v_rcp_f32_e32 v3, v3
	v_lshlrev_b32_e32 v8, 16, v64
	v_and_b32_e32 v9, 0xffff0000, v64
	v_lshlrev_b32_e32 v10, 16, v68
	v_and_b32_e32 v11, 0xffff0000, v68
	v_pk_fma_f32 v[4:5], v[4:5], v[10:11], v[8:9]
	v_lshlrev_b32_e32 v8, 16, v65
	v_and_b32_e32 v9, 0xffff0000, v65
	v_lshlrev_b32_e32 v10, 16, v69
	v_and_b32_e32 v11, 0xffff0000, v69
	v_pk_fma_f32 v[6:7], v[6:7], v[10:11], v[8:9]
	v_lshlrev_b32_e32 v8, 16, v66
	v_and_b32_e32 v9, 0xffff0000, v66
	v_lshlrev_b32_e32 v10, 16, v70
	v_and_b32_e32 v11, 0xffff0000, v70
	v_pk_fma_f32 v[0:1], v[0:1], v[10:11], v[8:9]
	v_lshlrev_b32_e32 v8, 16, v67
	v_and_b32_e32 v9, 0xffff0000, v67
	v_lshlrev_b32_e32 v10, 16, v71
	v_and_b32_e32 v11, 0xffff0000, v71
	s_andn2_b64 vcc, exec, s[4:5]
	s_mov_b64 s[4:5], -1
	flat_store_dwordx4 v[16:17], v[12:15]
	v_pk_fma_f32 v[2:3], v[2:3], v[10:11], v[8:9]
	flat_store_dwordx4 v[16:17], v[4:7] offset:128
	flat_store_dwordx4 v[16:17], v[0:3] offset:144
	s_cbranch_vccnz .LBB0_803
	s_and_b64 vcc, exec, s[0:1]
	s_cbranch_vccnz .LBB0_802
	s_barrier
	s_branch .LBB0_802
